# first half-step: K-base hop + tile DMA issue block moved from between QK and PV to behind PV (QK flows straight into PV)
# baseline (speedup 1.0000x reference)
; __device__ __forceinline__ void finishSM(f32x16& p0, f32x16& p1, float alpha, float& l_reg, bf16x8& pa0, bf16x8& pa1, bf16x8& pa2, bf16x8& pa3) {
;     for (int r = 0; r < 16; ++r) p1[r] = __builtin_amdgcn_exp2f(p1[r]);
;     float ps = 0; for (int r = 0; r < 16; ++r) ps += p0[r]; for (int r = 0; r < 16; ++r) ps += p1[r];
;     { auto rr = __builtin_amdgcn_permlane32_swap(__float_as_uint(ps), __float_as_uint(ps), false, false);
;       ps = __uint_as_float(rr[0]) + __uint_as_float(rr[1]); }
;     l_reg = l_reg * alpha + ps;
;     ...
;     PK4(p0, 0, pa0); PK4(p0, 8, pa1); PK4(p1, 0, pa2); PK4(p1, 8, pa3);
; template <int KB>
; __device__ __forceinline__ void qkt(f32x16& p0, f32x16& p1, const char* K_lds, int r32, int hi, const bf16x8* qr) {
;     p0 = f32x16{}; p1 = f32x16{};
;     const char* kb[4];
; #pragma unroll
;     for (int dd = 0; dd < 4; ++dd) kb[dd] = K_lds + KB * SHM_K + KSWZ(r32, (dd * 16 + hi * 8) * 2);
; #pragma unroll
;     for (int d0 = 0; d0 < 8; ++d0) { const char* a = kb[d0 & 3] + (d0 >> 2) * 128;
;         bf16x8 b0 = *reinterpret_cast<const bf16x8*>(a);
;         bf16x8 b1 = *reinterpret_cast<const bf16x8*>(a + 32 * 256);
;         p0 = __builtin_amdgcn_mfma_f32_32x32x16_bf16(b0, qr[d0], p0, 0, 0, 0);
;         p1 = __builtin_amdgcn_mfma_f32_32x32x16_bf16(b1, qr[d0], p1, 0, 0, 0); }
; }
; template <int VB>
; __device__ __forceinline__ void pv_tile(f32x16* o, int vb0, bf16x8 pa0, bf16x8 pa1, bf16x8 pa2, bf16x8 pa3) {
;     ...
;     PV_D0(0); PV_D0(1); PV_D0(2); PV_D0(3);
.LBB0_89:
	ds_read_b128 v[66:69], v169 offset:49152
	ds_read_b128 v[70:73], v169 offset:57344
	ds_read_b128 v[100:103], v193 offset:49152
	ds_read_b128 v[136:139], v193 offset:57344
	ds_read_b128 v[234:237], v194 offset:49152
	ds_read_b128 v[238:241], v194 offset:57344
	v_add_f32_e32 v148, 0, v231
	v_add_f32_e32 v148, v233, v148
	v_add_f32_e32 v148, v229, v148
	v_add_f32_e32 v148, v232, v148
	v_add_f32_e32 v148, v228, v148
	v_add_f32_e32 v148, v230, v148
	v_add_f32_e32 v148, v226, v148
	v_add_f32_e32 v148, v227, v148
	v_add_f32_e32 v148, v223, v148
	v_add_f32_e32 v148, v225, v148
	v_add_f32_e32 v148, v209, v148
	v_add_f32_e32 v148, v224, v148
	v_add_f32_e32 v148, v206, v148
	v_add_f32_e32 v148, v208, v148
	v_add_f32_e32 v148, v205, v148
	v_add_f32_e32 v148, v207, v148
	v_exp_f32_e32 v140, v152
	v_exp_f32_e32 v141, v153
	v_exp_f32_e32 v142, v180
	v_exp_f32_e32 v143, v181
	s_waitcnt lgkmcnt(5)
	v_mfma_f32_32x32x16_bf16 v[82:97], v[66:69], v[132:135], 0
	v_exp_f32_e32 v144, v160
	v_exp_f32_e32 v145, v161
	v_exp_f32_e32 v146, v154
	v_exp_f32_e32 v147, v155
	s_waitcnt lgkmcnt(4)
	v_mfma_f32_32x32x16_bf16 v[66:81], v[70:73], v[132:135], 0
	v_exp_f32_e32 v178, v178
	v_exp_f32_e32 v179, v179
	v_exp_f32_e32 v162, v162
	v_exp_f32_e32 v163, v163
	s_waitcnt lgkmcnt(3)
	v_mfma_f32_32x32x16_bf16 v[82:97], v[100:103], v[128:131], v[82:97]
	v_add_f32_e32 v148, v178, v148
	v_add_f32_e32 v148, v179, v148
	v_add_f32_e32 v148, v162, v148
	v_exp_f32_e32 v158, v158
	s_waitcnt lgkmcnt(2)
	v_mfma_f32_32x32x16_bf16 v[66:81], v[136:139], v[128:131], v[66:81]
	v_exp_f32_e32 v159, v159
	v_exp_f32_e32 v156, v156
	v_exp_f32_e32 v157, v157
	v_add_f32_e32 v148, v163, v148
	ds_read_b128 v[100:103], v195 offset:49152
	ds_read_b128 v[136:139], v195 offset:57344
	s_waitcnt lgkmcnt(3)
	v_mfma_f32_32x32x16_bf16 v[82:97], v[234:237], v[124:127], v[82:97]
	v_add_f32_e32 v148, v158, v148
	v_add_f32_e32 v148, v159, v148
	v_add_f32_e32 v148, v156, v148
	v_add_f32_e32 v148, v157, v148
	s_waitcnt lgkmcnt(2)
	v_mfma_f32_32x32x16_bf16 v[66:81], v[238:241], v[124:127], v[66:81]
	v_add_f32_e32 v148, v140, v148
	v_add_f32_e32 v148, v141, v148
	v_add_f32_e32 v148, v142, v148
	v_add_f32_e32 v148, v143, v148
	ds_read_b128 v[234:237], v169 offset:49280
	ds_read_b128 v[238:241], v169 offset:57472
	s_waitcnt lgkmcnt(3)
	v_mfma_f32_32x32x16_bf16 v[82:97], v[100:103], v[120:123], v[82:97]
	v_add_f32_e32 v148, v144, v148
	v_add_f32_e32 v148, v145, v148
	v_add_f32_e32 v148, v146, v148
	v_add_f32_e32 v199, v147, v148
	s_waitcnt lgkmcnt(2)
	v_mfma_f32_32x32x16_bf16 v[66:81], v[136:139], v[120:123], v[66:81]
	v_mov_b32_e32 v200, v199
	s_nop 1
	v_permlane32_swap_b32_e32 v199, v200
	v_cvt_pk_bf16_f32 v148, v231, v233
	v_cvt_pk_bf16_f32 v149, v229, v232
	v_cvt_pk_bf16_f32 v150, v228, v230
	ds_read_b128 v[100:103], v193 offset:49280
	ds_read_b128 v[136:139], v193 offset:57472
	s_waitcnt lgkmcnt(3)
	v_mfma_f32_32x32x16_bf16 v[82:97], v[234:237], v[116:119], v[82:97]
	v_cvt_pk_bf16_f32 v151, v226, v227
	v_cvt_pk_bf16_f32 v152, v223, v225
	v_cvt_pk_bf16_f32 v153, v209, v224
	s_waitcnt lgkmcnt(2)
	v_mfma_f32_32x32x16_bf16 v[66:81], v[238:241], v[116:119], v[66:81]
	v_cvt_pk_bf16_f32 v154, v206, v208
	v_cvt_pk_bf16_f32 v155, v205, v207
	v_cvt_pk_bf16_f32 v158, v158, v159
	ds_read_b128 v[234:237], v194 offset:49280
	ds_read_b128 v[238:241], v194 offset:57472
	s_waitcnt lgkmcnt(3)
	v_mfma_f32_32x32x16_bf16 v[82:97], v[100:103], v[112:115], v[82:97]
	v_cvt_pk_bf16_f32 v159, v156, v157
	v_cvt_pk_bf16_f32 v156, v178, v179
	v_cvt_pk_bf16_f32 v157, v162, v163
	s_waitcnt lgkmcnt(2)
	v_mfma_f32_32x32x16_bf16 v[66:81], v[136:139], v[112:115], v[66:81]
	v_cvt_pk_bf16_f32 v160, v140, v141
	v_cvt_pk_bf16_f32 v161, v142, v143
	v_cvt_pk_bf16_f32 v162, v144, v145
	ds_read_b128 v[100:103], v195 offset:49280
	ds_read_b128 v[136:139], v195 offset:57472
	ds_read_b64_tr_b16 v[172:173], v185 offset:0
	ds_read_b64_tr_b16 v[174:175], v185 offset:0x800
	ds_read_b64_tr_b16 v[202:203], v185 offset:0x1000
	ds_read_b64_tr_b16 v[204:205], v185 offset:0x1800
	ds_read_b64_tr_b16 v[206:207], v185 offset:0x2000
	ds_read_b64_tr_b16 v[208:209], v185 offset:0x2800
	ds_read_b64_tr_b16 v[224:225], v185 offset:0x3000
	ds_read_b64_tr_b16 v[226:227], v185 offset:0x3800
	s_waitcnt lgkmcnt(11)
	v_mfma_f32_32x32x16_bf16 v[82:97], v[234:237], v[108:111], v[82:97]
	v_cvt_pk_bf16_f32 v163, v146, v147
	s_nop 0
	v_permlane32_swap_b32_e32 v148, v150
	v_permlane32_swap_b32_e32 v149, v151
	s_waitcnt lgkmcnt(10)
	v_mfma_f32_32x32x16_bf16 v[66:81], v[238:241], v[108:111], v[66:81]
	v_permlane32_swap_b32_e32 v152, v154
	v_permlane32_swap_b32_e32 v153, v155
	v_permlane32_swap_b32_e32 v156, v158
	s_waitcnt lgkmcnt(9)
	v_mfma_f32_32x32x16_bf16 v[82:97], v[100:103], v[104:107], v[82:97]
	v_permlane32_swap_b32_e32 v157, v159
	v_permlane32_swap_b32_e32 v160, v162
	v_permlane32_swap_b32_e32 v161, v163
	s_waitcnt lgkmcnt(8)
	v_mfma_f32_32x32x16_bf16 v[66:81], v[136:139], v[104:107], v[66:81]
	s_nop 0
	s_waitcnt lgkmcnt(6)
	v_mfma_f32_32x32x16_bf16 v[50:65], v[148:151], v[172:175], v[50:65]
	ds_read_b64_tr_b16 v[172:173], v185 offset:0x200
	ds_read_b64_tr_b16 v[174:175], v185 offset:0xa00
	s_waitcnt lgkmcnt(6)
	v_mfma_f32_32x32x16_bf16 v[50:65], v[152:155], v[202:205], v[50:65]
	ds_read_b64_tr_b16 v[202:203], v185 offset:0x1200
	ds_read_b64_tr_b16 v[204:205], v185 offset:0x1a00
	s_waitcnt lgkmcnt(6)
	v_mfma_f32_32x32x16_bf16 v[50:65], v[156:159], v[206:209], v[50:65]
	ds_read_b64_tr_b16 v[206:207], v185 offset:0x2200
	ds_read_b64_tr_b16 v[208:209], v185 offset:0x2a00
	s_waitcnt lgkmcnt(6)
; __device__ __forceinline__ void mask_tile(f32x16& p0, f32x16& p1, int dq, unsigned W) {
;     const float NEG = -__builtin_inff();
; #pragma unroll
;     for (int r = 0; r < 16; ++r) {
;         const int c = (r & 3) + 8 * (r >> 2);
;         if ((unsigned)(dq - c) >= W) p0[r] = NEG;
;         if ((unsigned)(dq - c - 32) >= W) p1[r] = NEG;
;     }
; }
; template <int VB>
; __device__ __forceinline__ void pv_tile(f32x16* o, int vb0, bf16x8 pa0, bf16x8 pa1, bf16x8 pa2, bf16x8 pa3) {
;     ...
;     PV_D0(0); PV_D0(1); PV_D0(2); PV_D0(3);
	v_mfma_f32_32x32x16_bf16 v[50:65], v[160:163], v[224:227], v[50:65]
	ds_read_b64_tr_b16 v[224:225], v185 offset:0x3200
	ds_read_b64_tr_b16 v[226:227], v185 offset:0x3a00
	s_waitcnt lgkmcnt(6)
	v_mfma_f32_32x32x16_bf16 v[34:49], v[148:151], v[172:175], v[34:49]
	ds_read_b64_tr_b16 v[172:173], v185 offset:0x400
	ds_read_b64_tr_b16 v[174:175], v185 offset:0xc00
	s_waitcnt lgkmcnt(6)
	v_mfma_f32_32x32x16_bf16 v[34:49], v[152:155], v[202:205], v[34:49]
	ds_read_b64_tr_b16 v[202:203], v185 offset:0x1400
	ds_read_b64_tr_b16 v[204:205], v185 offset:0x1c00
	s_waitcnt lgkmcnt(6)
	v_mfma_f32_32x32x16_bf16 v[34:49], v[156:159], v[206:209], v[34:49]
	ds_read_b64_tr_b16 v[206:207], v185 offset:0x2400
	ds_read_b64_tr_b16 v[208:209], v185 offset:0x2c00
	s_waitcnt lgkmcnt(6)
	v_mfma_f32_32x32x16_bf16 v[34:49], v[160:163], v[224:227], v[34:49]
	ds_read_b64_tr_b16 v[224:225], v185 offset:0x3400
	ds_read_b64_tr_b16 v[226:227], v185 offset:0x3c00
	s_waitcnt lgkmcnt(6)
	v_mfma_f32_32x32x16_bf16 v[18:33], v[148:151], v[172:175], v[18:33]
	ds_read_b64_tr_b16 v[172:173], v185 offset:0x600
	ds_read_b64_tr_b16 v[174:175], v185 offset:0xe00
	s_waitcnt lgkmcnt(6)
	v_mfma_f32_32x32x16_bf16 v[18:33], v[152:155], v[202:205], v[18:33]
	ds_read_b64_tr_b16 v[202:203], v185 offset:0x1600
	ds_read_b64_tr_b16 v[204:205], v185 offset:0x1e00
	s_waitcnt lgkmcnt(6)
	v_mfma_f32_32x32x16_bf16 v[18:33], v[156:159], v[206:209], v[18:33]
	ds_read_b64_tr_b16 v[206:207], v185 offset:0x2600
	ds_read_b64_tr_b16 v[208:209], v185 offset:0x2e00
	s_waitcnt lgkmcnt(6)
	v_mfma_f32_32x32x16_bf16 v[18:33], v[160:163], v[224:227], v[18:33]
	ds_read_b64_tr_b16 v[224:225], v185 offset:0x3600
	ds_read_b64_tr_b16 v[226:227], v185 offset:0x3e00
	s_waitcnt lgkmcnt(6)
	v_mfma_f32_32x32x16_bf16 v[2:17], v[148:151], v[172:175], v[2:17]
	s_cmp_le_i32 s7, s6
	s_waitcnt lgkmcnt(4)
	v_mfma_f32_32x32x16_bf16 v[2:17], v[152:155], v[202:205], v[2:17]
	s_waitcnt lgkmcnt(2)
	v_mfma_f32_32x32x16_bf16 v[2:17], v[156:159], v[206:209], v[2:17]
	s_waitcnt lgkmcnt(0)
	v_mfma_f32_32x32x16_bf16 v[2:17], v[160:163], v[224:227], v[2:17]
	v_add_u32_e32 v169, s100, v169
	v_add_u32_e32 v193, s100, v193
	v_add_u32_e32 v194, s100, v194
	v_add_u32_e32 v195, s100, v195
	s_sub_i32 s100, 0, s100
	s_sub_i32 m0, 0, s100
	s_max_i32 m0, m0, 0
	s_add_i32 m0, m0, s32
	s_add_i32 m0, m0, 0x4000
	s_nop 0
	global_load_lds_dwordx4 v[244:245], off
	s_add_i32 m0, m0, 0x2000
	s_nop 0
	global_load_lds_dwordx4 v[246:247], off
	v_lshl_add_u64 v[244:245], v[244:245], 0, v[250:251]
	v_lshl_add_u64 v[246:247], v[246:247], 0, v[250:251]
	s_sub_i32 m0, 0, s100
	s_max_i32 m0, m0, 0
	s_add_i32 m0, m0, s32
	s_add_i32 m0, m0, s32
	s_sub_i32 m0, m0, 0x10000
	s_nop 0
	global_load_lds_dwordx4 v[248:249], off
	s_add_i32 m0, m0, 896
	s_nop 0
	global_load_lds_dwordx4 v[248:249], off offset:128
	v_lshl_add_u64 v[248:249], v[248:249], 0, v[250:251]
	s_cmp_le_i32 s7, s6
	s_cbranch_scc1 .LBB0_91
	v_add_u32_e32 v148, 0x4000007b, v197
	v_cmp_gt_u32_e32 vcc, 2.0, v148
	v_add_u32_e32 v148, 0x5b, v197
	s_nop 0
	v_cndmask_b32_e32 v82, v220, v82, vcc
	v_cmp_lt_u32_e32 vcc, s33, v148
	v_add_u32_e32 v148, 0x7a, v197
	s_nop 0
	v_cndmask_b32_e32 v66, v220, v66, vcc
	v_cmp_lt_u32_e32 vcc, s33, v148
	v_add_u32_e32 v148, 0x5a, v197
	s_nop 0
	v_cndmask_b32_e32 v83, v220, v83, vcc
	v_cmp_lt_u32_e32 vcc, s33, v148
	v_add_u32_e32 v148, 0x79, v197
	s_nop 0
	v_cndmask_b32_e32 v67, v220, v67, vcc
	v_cmp_lt_u32_e32 vcc, s33, v148
	v_add_u32_e32 v148, 0x59, v197
	s_nop 0
	v_cndmask_b32_e32 v84, v220, v84, vcc
	v_cmp_lt_u32_e32 vcc, s33, v148
	v_add_u32_e32 v148, 0x78, v197
	s_nop 0
	v_cndmask_b32_e32 v68, v220, v68, vcc
	v_cmp_lt_u32_e32 vcc, s33, v148
	v_add_u32_e32 v148, 0x58, v197
	s_nop 0
	v_cndmask_b32_e32 v85, v220, v85, vcc
	v_cmp_lt_u32_e32 vcc, s33, v148
	v_add_u32_e32 v148, 0x73, v197
	s_nop 0
	v_cndmask_b32_e32 v69, v220, v69, vcc
	v_cmp_lt_u32_e32 vcc, s33, v148
	v_add_u32_e32 v148, 0x53, v197
	s_nop 0
	v_cndmask_b32_e32 v86, v220, v86, vcc
	v_cmp_lt_u32_e32 vcc, s33, v148
	v_add_u32_e32 v148, 0x72, v197
	s_nop 0
	v_cndmask_b32_e32 v70, v220, v70, vcc
	v_cmp_lt_u32_e32 vcc, s33, v148
	v_add_u32_e32 v148, 0x52, v197
	s_nop 0
	v_cndmask_b32_e32 v87, v220, v87, vcc
	v_cmp_lt_u32_e32 vcc, s33, v148
	v_add_u32_e32 v148, 0x71, v197
	s_nop 0
	v_cndmask_b32_e32 v71, v220, v71, vcc
	v_cmp_lt_u32_e32 vcc, s33, v148
	v_add_u32_e32 v148, 0x51, v197
	s_nop 0
	v_cndmask_b32_e32 v88, v220, v88, vcc
	v_cmp_lt_u32_e32 vcc, s33, v148
	v_add_u32_e32 v148, 0x70, v197
	s_nop 0
	v_cndmask_b32_e32 v72, v220, v72, vcc
	v_cmp_lt_u32_e32 vcc, s33, v148
	v_add_u32_e32 v148, 0x50, v197
	s_nop 0
	v_cndmask_b32_e32 v89, v220, v89, vcc
	v_cmp_lt_u32_e32 vcc, s33, v148
	v_add_u32_e32 v148, 0x6b, v197
	s_nop 0
	v_cndmask_b32_e32 v73, v220, v73, vcc
	v_cmp_lt_u32_e32 vcc, s33, v148
	v_add_u32_e32 v148, 0x4b, v197
	s_nop 0
	v_cndmask_b32_e32 v90, v220, v90, vcc
	v_cmp_lt_u32_e32 vcc, s33, v148
	v_add_u32_e32 v148, 0x6a, v197
	s_nop 0
	v_cndmask_b32_e32 v74, v220, v74, vcc
	v_cmp_lt_u32_e32 vcc, s33, v148
	v_add_u32_e32 v148, 0x4a, v197
	s_nop 0
	v_cndmask_b32_e32 v91, v220, v91, vcc
	v_cmp_lt_u32_e32 vcc, s33, v148
	v_add_u32_e32 v148, 0x69, v197
	s_nop 0
	v_cndmask_b32_e32 v75, v220, v75, vcc
	v_cmp_lt_u32_e32 vcc, s33, v148
	v_add_u32_e32 v148, 0x49, v197
	s_nop 0
	v_cndmask_b32_e32 v92, v220, v92, vcc
	v_cmp_lt_u32_e32 vcc, s33, v148
	v_add_u32_e32 v148, 0x68, v197
	s_nop 0
	v_cndmask_b32_e32 v76, v220, v76, vcc
	v_cmp_lt_u32_e32 vcc, s33, v148
	v_add_u32_e32 v148, 0x48, v197
	s_nop 0
	v_cndmask_b32_e32 v93, v220, v93, vcc
	v_cmp_lt_u32_e32 vcc, s33, v148
	v_add_u32_e32 v148, 0x63, v197
	s_nop 0
	v_cndmask_b32_e32 v77, v220, v77, vcc
	v_cmp_lt_u32_e32 vcc, s33, v148
	v_add_u32_e32 v148, 0x43, v197
	s_nop 0
	v_cndmask_b32_e32 v94, v220, v94, vcc
	v_cmp_lt_u32_e32 vcc, s33, v148
	v_add_u32_e32 v148, 0x62, v197
	s_nop 0
	v_cndmask_b32_e32 v78, v220, v78, vcc
	v_cmp_lt_u32_e32 vcc, s33, v148
	v_add_u32_e32 v148, 0x42, v197
	s_nop 0
	v_cndmask_b32_e32 v95, v220, v95, vcc
	v_cmp_lt_u32_e32 vcc, s33, v148
	v_add_u32_e32 v148, 0x61, v197
	s_nop 0
	v_cndmask_b32_e32 v79, v220, v79, vcc
	v_cmp_lt_u32_e32 vcc, s33, v148
	v_add_u32_e32 v148, 0x41, v197
	s_nop 0
	v_cndmask_b32_e32 v96, v220, v96, vcc
	v_cmp_lt_u32_e32 vcc, s33, v148
	v_add_u32_e32 v148, 0x60, v197
	s_nop 0
	v_cndmask_b32_e32 v80, v220, v80, vcc
	v_cmp_lt_u32_e32 vcc, s33, v148
	v_add_u32_e32 v148, 64, v197
	s_nop 0
	v_cndmask_b32_e32 v97, v220, v97, vcc
	v_cmp_lt_u32_e32 vcc, s33, v148
	s_nop 1
	v_cndmask_b32_e32 v81, v220, v81, vcc
